# attention: DMA pieces between MFMAs, mask reference constant per unit (one VALU per tile fewer); on top of peeled GEMM loops and epilogue cleanups
# speedup vs baseline: 1.0109x; 1.0028x over previous
.Lat_resc_b0_ret:
	s_add_i32 s33, s33, 64
	s_add_i32 s0, s0, 1
	s_waitcnt vmcnt(0) lgkmcnt(0)
	s_barrier

.Lat_resc_b3_ret:
	s_add_i32 s33, s33, 64
	s_add_i32 s0, s0, 1
	s_cmp_eq_u32 s53, s0
	s_waitcnt vmcnt(0) lgkmcnt(0)
	s_barrier
	s_cbranch_scc0 .LBB0_1340
	v_exp_f32_e32 v64, v64
	v_exp_f32_e32 v65, v65
	v_add_f32_e32 v200, v200, v64
	v_exp_f32_e32 v66, v66
	v_add_f32_e32 v200, v200, v65
	v_exp_f32_e32 v67, v67
	v_add_f32_e32 v200, v200, v66
	v_exp_f32_e32 v68, v68
	v_add_f32_e32 v200, v200, v67
	v_exp_f32_e32 v69, v69
	v_add_f32_e32 v200, v200, v68
	v_exp_f32_e32 v70, v70
	v_add_f32_e32 v200, v200, v69
	v_exp_f32_e32 v71, v71
	v_add_f32_e32 v200, v200, v70
	v_exp_f32_e32 v72, v72
	v_add_f32_e32 v200, v200, v71
	v_exp_f32_e32 v73, v73
	v_add_f32_e32 v200, v200, v72
	v_exp_f32_e32 v74, v74
	v_add_f32_e32 v200, v200, v73
	v_exp_f32_e32 v75, v75
	v_add_f32_e32 v200, v200, v74
	v_exp_f32_e32 v76, v76
	v_add_f32_e32 v200, v200, v75
	v_exp_f32_e32 v77, v77
	v_add_f32_e32 v200, v200, v76
	v_exp_f32_e32 v78, v78
	v_add_f32_e32 v200, v200, v77
	v_exp_f32_e32 v79, v79
	v_add_f32_e32 v200, v200, v78
	v_add_f32_e32 v200, v200, v79
	v_cvt_pk_bf16_f32 v236, v64, v65
	v_cvt_pk_bf16_f32 v237, v66, v67
	v_cvt_pk_bf16_f32 v238, v68, v69
	v_cvt_pk_bf16_f32 v239, v70, v71
	v_cvt_pk_bf16_f32 v240, v72, v73
	v_cvt_pk_bf16_f32 v241, v74, v75
	v_cvt_pk_bf16_f32 v242, v76, v77
	v_cvt_pk_bf16_f32 v243, v78, v79
	v_mov_b32_e32 v68, v236
	v_mov_b32_e32 v69, v237
	v_mov_b32_e32 v70, v238
	v_mov_b32_e32 v71, v239
	v_mov_b32_e32 v64, v240
	v_mov_b32_e32 v65, v241
	v_mov_b32_e32 v66, v242
	v_mov_b32_e32 v67, v243
	s_branch .LBB0_1332

.Lat_mask_a0:
	s_nop 7
	s_sub_i32 s4, s33, 63
	v_subrev_u32_e32 v173, s4, v197
	v_cmp_gt_i32_e64 s[4:5], 0, v173
	v_cmp_gt_i32_e64 s[6:7], 1, v173
	v_cmp_gt_i32_e64 s[8:9], 2, v173
	v_cmp_gt_i32_e64 s[10:11], 3, v173
	v_cmp_gt_i32_e64 s[12:13], 4, v173
	v_cmp_gt_i32_e64 s[14:15], 5, v173
	v_cmp_gt_i32_e64 s[16:17], 6, v173
	v_cmp_gt_i32_e64 s[18:19], 7, v173
	v_cndmask_b32_e64 v80, v80, v192, s[4:5]
	v_cndmask_b32_e64 v81, v81, v192, s[6:7]
	v_cndmask_b32_e64 v82, v82, v192, s[8:9]
	v_cndmask_b32_e64 v83, v83, v192, s[10:11]
	v_cndmask_b32_e64 v84, v84, v192, s[12:13]
	v_cndmask_b32_e64 v85, v85, v192, s[14:15]
	v_cndmask_b32_e64 v86, v86, v192, s[16:17]
	v_cndmask_b32_e64 v87, v87, v192, s[18:19]
	v_cmp_gt_i32_e64 s[4:5], 16, v173
	v_cmp_gt_i32_e64 s[6:7], 17, v173
	v_cmp_gt_i32_e64 s[8:9], 18, v173
	v_cmp_gt_i32_e64 s[10:11], 19, v173
	v_cmp_gt_i32_e64 s[12:13], 20, v173
	v_cmp_gt_i32_e64 s[14:15], 21, v173
	v_cmp_gt_i32_e64 s[16:17], 22, v173
	v_cmp_gt_i32_e64 s[18:19], 23, v173
	v_cndmask_b32_e64 v88, v88, v192, s[4:5]
	v_cndmask_b32_e64 v89, v89, v192, s[6:7]
	v_cndmask_b32_e64 v90, v90, v192, s[8:9]
	v_cndmask_b32_e64 v91, v91, v192, s[10:11]
	v_cndmask_b32_e64 v92, v92, v192, s[12:13]
	v_cndmask_b32_e64 v93, v93, v192, s[14:15]
	v_cndmask_b32_e64 v94, v94, v192, s[16:17]
	v_cndmask_b32_e64 v95, v95, v192, s[18:19]
	s_branch .Lat_mask_a0_ret
.Lat_mask_b0:
	s_nop 7
	s_sub_i32 s4, s33, 63
	v_subrev_u32_e32 v173, s4, v197
	v_cmp_gt_i32_e64 s[4:5], 32, v173
	v_cmp_gt_i32_e64 s[6:7], 33, v173
	v_cmp_gt_i32_e64 s[8:9], 34, v173
	v_cmp_gt_i32_e64 s[10:11], 35, v173
	v_cmp_gt_i32_e64 s[12:13], 36, v173
	v_cmp_gt_i32_e64 s[14:15], 37, v173
	v_cmp_gt_i32_e64 s[16:17], 38, v173
	v_cmp_gt_i32_e64 s[18:19], 39, v173
	v_cndmask_b32_e64 v64, v64, v192, s[4:5]
	v_cndmask_b32_e64 v65, v65, v192, s[6:7]
	v_cndmask_b32_e64 v66, v66, v192, s[8:9]
	v_cndmask_b32_e64 v67, v67, v192, s[10:11]
	v_cndmask_b32_e64 v68, v68, v192, s[12:13]
	v_cndmask_b32_e64 v69, v69, v192, s[14:15]
	v_cndmask_b32_e64 v70, v70, v192, s[16:17]
	v_cndmask_b32_e64 v71, v71, v192, s[18:19]
	v_cmp_gt_i32_e64 s[4:5], 48, v173
	v_cmp_gt_i32_e64 s[6:7], 49, v173
	v_cmp_gt_i32_e64 s[8:9], 50, v173
	v_cmp_gt_i32_e64 s[10:11], 51, v173
	v_cmp_gt_i32_e64 s[12:13], 52, v173
	v_cmp_gt_i32_e64 s[14:15], 53, v173
	v_cmp_gt_i32_e64 s[16:17], 54, v173
	v_cmp_gt_i32_e64 s[18:19], 55, v173
	v_cndmask_b32_e64 v72, v72, v192, s[4:5]
	v_cndmask_b32_e64 v73, v73, v192, s[6:7]
	v_cndmask_b32_e64 v74, v74, v192, s[8:9]
	v_cndmask_b32_e64 v75, v75, v192, s[10:11]
	v_cndmask_b32_e64 v76, v76, v192, s[12:13]
	v_cndmask_b32_e64 v77, v77, v192, s[14:15]
	v_cndmask_b32_e64 v78, v78, v192, s[16:17]
	v_cndmask_b32_e64 v79, v79, v192, s[18:19]
	s_branch .Lat_mask_b0_ret
